# combined: merge gate loads widened, upproj and attention output stores widened (permlane swaps), stand-alone PV tail with 4 rotating LDS read buffers
# speedup vs baseline: 1.0285x; 1.0005x over previous
.LBB0_379:
	v_cmp_ge_i32_e32 vcc, s13, v246
	s_and_saveexec_b64 s[14:15], vcc
	s_xor_b64 s[84:85], exec, s[14:15]
	s_cbranch_execz .LBB0_381
	v_add_u32_e32 v0, v204, v247
	ds_read_b128 v[96:99], v0 offset:13312
	ds_read_b128 v[100:103], v0 offset:17920
	ds_read_b128 v[104:107], v0 offset:22528
	ds_read_b128 v[108:111], v0 offset:27136
	s_waitcnt lgkmcnt(3)
	v_mfma_f32_32x32x16_bf16 v[80:95], v[96:99], v[180:183], v[80:95]
	ds_read_b128 v[96:99], v0 offset:13344
	s_waitcnt lgkmcnt(3)
	v_mfma_f32_32x32x16_bf16 v[64:79], v[100:103], v[180:183], v[64:79]
	ds_read_b128 v[100:103], v0 offset:17952
	s_waitcnt lgkmcnt(3)
	v_mfma_f32_32x32x16_bf16 v[48:63], v[104:107], v[180:183], v[48:63]
	ds_read_b128 v[104:107], v0 offset:22560
	s_waitcnt lgkmcnt(3)
	v_mfma_f32_32x32x16_bf16 v[32:47], v[108:111], v[180:183], v[32:47]
	ds_read_b128 v[108:111], v0 offset:27168
	s_waitcnt lgkmcnt(3)
	v_mfma_f32_32x32x16_bf16 v[80:95], v[96:99], v[184:187], v[80:95]
	ds_read_b128 v[96:99], v0 offset:13376
	s_waitcnt lgkmcnt(3)
	v_mfma_f32_32x32x16_bf16 v[64:79], v[100:103], v[184:187], v[64:79]
	ds_read_b128 v[100:103], v0 offset:17984
	s_waitcnt lgkmcnt(3)
	v_mfma_f32_32x32x16_bf16 v[48:63], v[104:107], v[184:187], v[48:63]
	ds_read_b128 v[104:107], v0 offset:22592
	s_waitcnt lgkmcnt(3)
	v_mfma_f32_32x32x16_bf16 v[32:47], v[108:111], v[184:187], v[32:47]
	ds_read_b128 v[108:111], v0 offset:27200
	s_waitcnt lgkmcnt(3)
	v_mfma_f32_32x32x16_bf16 v[80:95], v[96:99], v[188:191], v[80:95]
	ds_read_b128 v[96:99], v0 offset:13408
	s_waitcnt lgkmcnt(3)
	v_mfma_f32_32x32x16_bf16 v[64:79], v[100:103], v[188:191], v[64:79]
	ds_read_b128 v[100:103], v0 offset:18016
	s_waitcnt lgkmcnt(3)
	v_mfma_f32_32x32x16_bf16 v[48:63], v[104:107], v[188:191], v[48:63]
	ds_read_b128 v[104:107], v0 offset:22624
	s_waitcnt lgkmcnt(3)
	v_mfma_f32_32x32x16_bf16 v[32:47], v[108:111], v[188:191], v[32:47]
	ds_read_b128 v[108:111], v0 offset:27232
	s_waitcnt lgkmcnt(3)
	v_mfma_f32_32x32x16_bf16 v[80:95], v[96:99], v[192:195], v[80:95]
	s_waitcnt lgkmcnt(2)
	v_mfma_f32_32x32x16_bf16 v[64:79], v[100:103], v[192:195], v[64:79]
	s_waitcnt lgkmcnt(1)
	v_mfma_f32_32x32x16_bf16 v[48:63], v[104:107], v[192:195], v[48:63]
	s_waitcnt lgkmcnt(0)
	v_mfma_f32_32x32x16_bf16 v[32:47], v[108:111], v[192:195], v[32:47]

.LBB0_393:
	s_add_i32 s13, s11, -2
	v_cmp_ge_i32_e32 vcc, s13, v246
	v_add_u32_e32 v0, v204, v247
	s_and_saveexec_b64 s[14:15], vcc
	s_xor_b64 s[40:41], exec, s[14:15]
	s_cbranch_execz .LBB0_395
	ds_read_b128 v[96:99], v0 offset:45056
	ds_read_b128 v[100:103], v0 offset:49664
	ds_read_b128 v[104:107], v0 offset:54272
	ds_read_b128 v[108:111], v0 offset:58880
	s_waitcnt lgkmcnt(3)
	v_mfma_f32_32x32x16_bf16 v[80:95], v[96:99], v[2:5], v[80:95]
	ds_read_b128 v[96:99], v0 offset:45088
	s_waitcnt lgkmcnt(3)
	v_mfma_f32_32x32x16_bf16 v[64:79], v[100:103], v[2:5], v[64:79]
	ds_read_b128 v[100:103], v0 offset:49696
	s_waitcnt lgkmcnt(3)
	v_mfma_f32_32x32x16_bf16 v[48:63], v[104:107], v[2:5], v[48:63]
	ds_read_b128 v[104:107], v0 offset:54304
	s_waitcnt lgkmcnt(3)
	v_mfma_f32_32x32x16_bf16 v[32:47], v[108:111], v[2:5], v[32:47]
	ds_read_b128 v[108:111], v0 offset:58912
	s_waitcnt lgkmcnt(3)
	v_mfma_f32_32x32x16_bf16 v[80:95], v[96:99], v[6:9], v[80:95]
	ds_read_b128 v[96:99], v0 offset:45120
	s_waitcnt lgkmcnt(3)
	v_mfma_f32_32x32x16_bf16 v[64:79], v[100:103], v[6:9], v[64:79]
	ds_read_b128 v[100:103], v0 offset:49728
	s_waitcnt lgkmcnt(3)
	v_mfma_f32_32x32x16_bf16 v[48:63], v[104:107], v[6:9], v[48:63]
	ds_read_b128 v[104:107], v0 offset:54336
	s_waitcnt lgkmcnt(3)
	v_mfma_f32_32x32x16_bf16 v[32:47], v[108:111], v[6:9], v[32:47]
	ds_read_b128 v[108:111], v0 offset:58944
	s_waitcnt lgkmcnt(3)
	v_mfma_f32_32x32x16_bf16 v[80:95], v[96:99], v[10:13], v[80:95]
	ds_read_b128 v[96:99], v0 offset:45152
	s_waitcnt lgkmcnt(3)
	v_mfma_f32_32x32x16_bf16 v[64:79], v[100:103], v[10:13], v[64:79]
	ds_read_b128 v[100:103], v0 offset:49760
	s_waitcnt lgkmcnt(3)
	v_mfma_f32_32x32x16_bf16 v[48:63], v[104:107], v[10:13], v[48:63]
	ds_read_b128 v[104:107], v0 offset:54368
	s_waitcnt lgkmcnt(3)
	v_mfma_f32_32x32x16_bf16 v[32:47], v[108:111], v[10:13], v[32:47]
	ds_read_b128 v[108:111], v0 offset:58976
	s_waitcnt lgkmcnt(3)
	v_mfma_f32_32x32x16_bf16 v[80:95], v[96:99], v[196:199], v[80:95]
	s_waitcnt lgkmcnt(2)
	v_mfma_f32_32x32x16_bf16 v[64:79], v[100:103], v[196:199], v[64:79]
	s_waitcnt lgkmcnt(1)
	v_mfma_f32_32x32x16_bf16 v[48:63], v[104:107], v[196:199], v[48:63]
	s_waitcnt lgkmcnt(0)
	v_mfma_f32_32x32x16_bf16 v[32:47], v[108:111], v[196:199], v[32:47]

.LBB0_413:
	v_cmp_ge_i32_e32 vcc, s11, v221
	s_and_saveexec_b64 s[12:13], vcc
	s_xor_b64 s[84:85], exec, s[12:13]
	s_cbranch_execz .LBB0_415
	v_add_u32_e32 v0, v190, v222
	ds_read_b128 v[96:99], v0 offset:13312
	ds_read_b128 v[100:103], v0 offset:17920
	ds_read_b128 v[104:107], v0 offset:22528
	ds_read_b128 v[108:111], v0 offset:27136
	s_waitcnt lgkmcnt(3)
	v_mfma_f32_32x32x16_bf16 v[80:95], v[96:99], v[168:171], v[80:95]
	ds_read_b128 v[96:99], v0 offset:13344
	s_waitcnt lgkmcnt(3)
	v_mfma_f32_32x32x16_bf16 v[64:79], v[100:103], v[168:171], v[64:79]
	ds_read_b128 v[100:103], v0 offset:17952
	s_waitcnt lgkmcnt(3)
	v_mfma_f32_32x32x16_bf16 v[48:63], v[104:107], v[168:171], v[48:63]
	ds_read_b128 v[104:107], v0 offset:22560
	s_waitcnt lgkmcnt(3)
	v_mfma_f32_32x32x16_bf16 v[32:47], v[108:111], v[168:171], v[32:47]
	ds_read_b128 v[108:111], v0 offset:27168
	s_waitcnt lgkmcnt(3)
	v_mfma_f32_32x32x16_bf16 v[80:95], v[96:99], v[172:175], v[80:95]
	ds_read_b128 v[96:99], v0 offset:13376
	s_waitcnt lgkmcnt(3)
	v_mfma_f32_32x32x16_bf16 v[64:79], v[100:103], v[172:175], v[64:79]
	ds_read_b128 v[100:103], v0 offset:17984
	s_waitcnt lgkmcnt(3)
	v_mfma_f32_32x32x16_bf16 v[48:63], v[104:107], v[172:175], v[48:63]
	ds_read_b128 v[104:107], v0 offset:22592
	s_waitcnt lgkmcnt(3)
	v_mfma_f32_32x32x16_bf16 v[32:47], v[108:111], v[172:175], v[32:47]
	ds_read_b128 v[108:111], v0 offset:27200
	s_waitcnt lgkmcnt(3)
	v_mfma_f32_32x32x16_bf16 v[80:95], v[96:99], v[176:179], v[80:95]
	ds_read_b128 v[96:99], v0 offset:13408
	s_waitcnt lgkmcnt(3)
	v_mfma_f32_32x32x16_bf16 v[64:79], v[100:103], v[176:179], v[64:79]
	ds_read_b128 v[100:103], v0 offset:18016
	s_waitcnt lgkmcnt(3)
	v_mfma_f32_32x32x16_bf16 v[48:63], v[104:107], v[176:179], v[48:63]
	ds_read_b128 v[104:107], v0 offset:22624
	s_waitcnt lgkmcnt(3)
	v_mfma_f32_32x32x16_bf16 v[32:47], v[108:111], v[176:179], v[32:47]
	ds_read_b128 v[108:111], v0 offset:27232
	s_waitcnt lgkmcnt(3)
	v_mfma_f32_32x32x16_bf16 v[80:95], v[96:99], v[180:183], v[80:95]
	s_waitcnt lgkmcnt(2)
	v_mfma_f32_32x32x16_bf16 v[64:79], v[100:103], v[180:183], v[64:79]
	s_waitcnt lgkmcnt(1)
	v_mfma_f32_32x32x16_bf16 v[48:63], v[104:107], v[180:183], v[48:63]
	s_waitcnt lgkmcnt(0)
	v_mfma_f32_32x32x16_bf16 v[32:47], v[108:111], v[180:183], v[32:47]

.LBB0_427:
	s_add_i32 s11, s9, -2
	v_cmp_ge_i32_e32 vcc, s11, v221
	v_add_u32_e32 v0, v190, v222
	s_and_saveexec_b64 s[12:13], vcc
	s_xor_b64 s[40:41], exec, s[12:13]
	s_cbranch_execz .LBB0_429
	ds_read_b128 v[96:99], v0 offset:45056
	ds_read_b128 v[100:103], v0 offset:49664
	ds_read_b128 v[104:107], v0 offset:54272
	ds_read_b128 v[108:111], v0 offset:58880
	s_waitcnt lgkmcnt(3)
	v_mfma_f32_32x32x16_bf16 v[80:95], v[96:99], v[2:5], v[80:95]
	ds_read_b128 v[96:99], v0 offset:45088
	s_waitcnt lgkmcnt(3)
	v_mfma_f32_32x32x16_bf16 v[64:79], v[100:103], v[2:5], v[64:79]
	ds_read_b128 v[100:103], v0 offset:49696
	s_waitcnt lgkmcnt(3)
	v_mfma_f32_32x32x16_bf16 v[48:63], v[104:107], v[2:5], v[48:63]
	ds_read_b128 v[104:107], v0 offset:54304
	s_waitcnt lgkmcnt(3)
	v_mfma_f32_32x32x16_bf16 v[32:47], v[108:111], v[2:5], v[32:47]
	ds_read_b128 v[108:111], v0 offset:58912
	s_waitcnt lgkmcnt(3)
	v_mfma_f32_32x32x16_bf16 v[80:95], v[96:99], v[6:9], v[80:95]
	ds_read_b128 v[96:99], v0 offset:45120
	s_waitcnt lgkmcnt(3)
	v_mfma_f32_32x32x16_bf16 v[64:79], v[100:103], v[6:9], v[64:79]
	ds_read_b128 v[100:103], v0 offset:49728
	s_waitcnt lgkmcnt(3)
	v_mfma_f32_32x32x16_bf16 v[48:63], v[104:107], v[6:9], v[48:63]
	ds_read_b128 v[104:107], v0 offset:54336
	s_waitcnt lgkmcnt(3)
	v_mfma_f32_32x32x16_bf16 v[32:47], v[108:111], v[6:9], v[32:47]
	ds_read_b128 v[108:111], v0 offset:58944
	s_waitcnt lgkmcnt(3)
	v_mfma_f32_32x32x16_bf16 v[80:95], v[96:99], v[10:13], v[80:95]
	ds_read_b128 v[96:99], v0 offset:45152
	s_waitcnt lgkmcnt(3)
	v_mfma_f32_32x32x16_bf16 v[64:79], v[100:103], v[10:13], v[64:79]
	ds_read_b128 v[100:103], v0 offset:49760
	s_waitcnt lgkmcnt(3)
	v_mfma_f32_32x32x16_bf16 v[48:63], v[104:107], v[10:13], v[48:63]
	ds_read_b128 v[104:107], v0 offset:54368
	s_waitcnt lgkmcnt(3)
	v_mfma_f32_32x32x16_bf16 v[32:47], v[108:111], v[10:13], v[32:47]
	ds_read_b128 v[108:111], v0 offset:58976
	s_waitcnt lgkmcnt(3)
	v_mfma_f32_32x32x16_bf16 v[80:95], v[96:99], v[184:187], v[80:95]
	s_waitcnt lgkmcnt(2)
	v_mfma_f32_32x32x16_bf16 v[64:79], v[100:103], v[184:187], v[64:79]
	s_waitcnt lgkmcnt(1)
	v_mfma_f32_32x32x16_bf16 v[48:63], v[104:107], v[184:187], v[48:63]
	s_waitcnt lgkmcnt(0)
	v_mfma_f32_32x32x16_bf16 v[32:47], v[108:111], v[184:187], v[32:47]

; DI int otid() { int t = (int)__builtin_amdgcn_workitem_id_x(); asm volatile("" : "+v"(t)); return t; }
; DI void st_bf4(bf16_t* dst, f32x4 v) { u32x2 o; o.x = pk2(v[0], v[1]); o.y = pk2(v[2], v[3]); *(u32x2*)dst = o; }
; DI void attn_store(const f32x16 (&O)[4], bf16_t* dst  , int ld) {
;   const int lane = otid() & 63, l31 = lane & 31, hf = lane >> 5;
; #pragma unroll
;   for (int d = 0; d < 4; ++d)
; #pragma unroll
;     for (int g = 0; g < 4; ++g) {
;       const int dv = d * 32 + g * 8 + hf * 4;
;       f32x4 v = {O[d][4 * g], O[d][4 * g + 1], O[d][4 * g + 2], O[d][4 * g + 3]};
;       st_bf4(dst + (size_t)l31 * ld + dv, v);
;     }
.LBB0_432:
	v_and_b32_e32 v106, 32, v227
	v_lshrrev_b32_e32 v106, 2, v106
	v_mov_b32_e32 v107, 0
	s_nop 0
	v_lshlrev_b32_e32 v0, 10, v68
	v_and_b32_e32 v0, 0x7c00, v0
	v_lshl_add_u64 v[66:67], v[66:67], 0, v[0:1]
	v_lshrrev_b32_e32 v0, 2, v68
	v_and_b32_e32 v0, 8, v0
	v_lshl_add_u64 v[66:67], v[66:67], 0, v[0:1]
	v_cvt_pk_bf16_f32 v96, v2, v3
	v_cvt_pk_bf16_f32 v97, v4, v5
	v_cvt_pk_bf16_f32 v98, v6, v7
	v_cvt_pk_bf16_f32 v99, v8, v9
	v_lshl_add_u64 v[104:105], v[66:67], 0, v[106:107]
	s_nop 0
	v_permlane32_swap_b32_e32 v96, v98
	v_permlane32_swap_b32_e32 v97, v99
	global_store_dwordx4 v[104:105], v[96:99], off
	v_cvt_pk_bf16_f32 v100, v10, v11
	v_cvt_pk_bf16_f32 v101, v12, v13
	v_cvt_pk_bf16_f32 v102, v14, v15
	v_cvt_pk_bf16_f32 v103, v18, v19
	v_lshl_add_u64 v[104:105], v[66:67], 0, v[106:107]
	s_nop 0
	v_permlane32_swap_b32_e32 v100, v102
	v_permlane32_swap_b32_e32 v101, v103
	global_store_dwordx4 v[104:105], v[100:103], off offset:32
	v_cvt_pk_bf16_f32 v96, v16, v17
	v_cvt_pk_bf16_f32 v97, v20, v21
	v_cvt_pk_bf16_f32 v98, v22, v23
	v_cvt_pk_bf16_f32 v99, v24, v25
	v_lshl_add_u64 v[104:105], v[66:67], 0, v[106:107]
	s_nop 0
	v_permlane32_swap_b32_e32 v96, v98
	v_permlane32_swap_b32_e32 v97, v99
	global_store_dwordx4 v[104:105], v[96:99], off offset:64
	v_cvt_pk_bf16_f32 v100, v26, v27
	v_cvt_pk_bf16_f32 v101, v28, v29
	v_cvt_pk_bf16_f32 v102, v30, v31
	v_cvt_pk_bf16_f32 v103, v64, v65
	v_lshl_add_u64 v[104:105], v[66:67], 0, v[106:107]
	s_nop 0
	v_permlane32_swap_b32_e32 v100, v102
	v_permlane32_swap_b32_e32 v101, v103
	global_store_dwordx4 v[104:105], v[100:103], off offset:96
	v_cvt_pk_bf16_f32 v96, v48, v49
	v_cvt_pk_bf16_f32 v97, v50, v51
	v_cvt_pk_bf16_f32 v98, v52, v53
	v_cvt_pk_bf16_f32 v99, v54, v55
	v_lshl_add_u64 v[104:105], v[66:67], 0, v[106:107]
	s_nop 0
	v_permlane32_swap_b32_e32 v96, v98
	v_permlane32_swap_b32_e32 v97, v99
	global_store_dwordx4 v[104:105], v[96:99], off offset:128
	v_cvt_pk_bf16_f32 v100, v56, v57
	v_cvt_pk_bf16_f32 v101, v58, v59
	v_cvt_pk_bf16_f32 v102, v60, v61
	v_cvt_pk_bf16_f32 v103, v62, v63
	v_lshl_add_u64 v[104:105], v[66:67], 0, v[106:107]
	s_nop 0
	v_permlane32_swap_b32_e32 v100, v102
	v_permlane32_swap_b32_e32 v101, v103
	global_store_dwordx4 v[104:105], v[100:103], off offset:160
	v_cvt_pk_bf16_f32 v96, v32, v33
	v_cvt_pk_bf16_f32 v97, v34, v35
	v_cvt_pk_bf16_f32 v98, v36, v37
	v_cvt_pk_bf16_f32 v99, v38, v39
	v_lshl_add_u64 v[104:105], v[66:67], 0, v[106:107]
	s_nop 0
	v_permlane32_swap_b32_e32 v96, v98
	v_permlane32_swap_b32_e32 v97, v99
	global_store_dwordx4 v[104:105], v[96:99], off offset:192
	s_mov_b64 s[0:1], 0
	v_cvt_pk_bf16_f32 v100, v40, v41
	v_cvt_pk_bf16_f32 v101, v42, v43
	v_cvt_pk_bf16_f32 v102, v44, v45
	v_cvt_pk_bf16_f32 v103, v46, v47
	v_lshl_add_u64 v[104:105], v[66:67], 0, v[106:107]
	s_nop 0
	v_permlane32_swap_b32_e32 v100, v102
	v_permlane32_swap_b32_e32 v101, v103
	global_store_dwordx4 v[104:105], v[100:103], off offset:224

; DI void st_bf4(bf16_t* dst, f32x4 v) { u32x2 o; o.x = pk2(v[0], v[1]); o.y = pk2(v[2], v[3]); *(u32x2*)dst = o; }
; DI void upproj_item(const Params& p, int l, int item, bf16_t* lds) {
;     ...
;     EPI_LOOP({ st_bf4(dst + (size_t)t * 384 + n0 + cl, v); })
;   } else {
;     item -= 384; const int mt = item / 6, nt = item % 6, m0 = mt * 128, n0 = nt * 128;
;     gemm_kloop<4>(acc, RB + (size_t)m0 * 768 + 384, 768, (const bf16_t*)(p.ws + OFF_W + (size_t)l * W_LAYER + W_KVUP) + (size_t)n0 * 256, 256, 256, lds, lds + 128 * 72);
;     bf16_t* dst = (bf16_t*)(p.ws + OFF_HB);
;     EPI_LOOP({ st_bf4(dst + (size_t)t * 768 + n0 + cl, v); })
.LBB0_842:
	v_and_b32_e32 v110, 16, v227
	v_lshrrev_b32_e32 v111, 1, v110
	v_add_u32_e32 v110, v110, v111
	v_mov_b32_e32 v111, 0
	v_mov_b64_e32 v[68:69], s[28:29]
	s_waitcnt vmcnt(6)
	v_mad_i64_i32 v[70:71], s[4:5], s26, v66, v[68:69]
	v_lshlrev_b64 v[72:73], 1, v[0:1]
	v_lshl_add_u64 v[70:71], v[70:71], 0, v[72:73]
	v_cvt_pk_bf16_f32 v2, v2, v3
	v_cvt_pk_bf16_f32 v3, v4, v5
	v_mov_b32_e32 v100, v2
	v_mov_b32_e32 v101, v3
	v_cvt_pk_bf16_f32 v2, v6, v7
	v_cvt_pk_bf16_f32 v3, v8, v9
	v_mov_b32_e32 v102, v2
	v_mov_b32_e32 v103, v3
	v_lshl_add_u64 v[108:109], v[70:71], 0, v[110:111]
	s_nop 0
	v_permlane16_swap_b32_e32 v100, v102
	v_permlane16_swap_b32_e32 v101, v103
	global_store_dwordx4 v[108:109], v[100:103], off
	v_cvt_pk_bf16_f32 v2, v10, v11
	v_cvt_pk_bf16_f32 v3, v12, v13
	v_mov_b32_e32 v104, v2
	v_mov_b32_e32 v105, v3
	v_cvt_pk_bf16_f32 v2, v22, v23
	v_cvt_pk_bf16_f32 v3, v24, v25
	v_or_b32_e32 v0, 16, v66
	v_mov_b32_e32 v106, v2
	v_mov_b32_e32 v107, v3
	v_lshl_add_u64 v[108:109], v[70:71], 0, v[110:111]
	s_nop 0
	v_permlane16_swap_b32_e32 v104, v106
	v_permlane16_swap_b32_e32 v105, v107
	global_store_dwordx4 v[108:109], v[104:107], off offset:64
	v_mad_i64_i32 v[2:3], s[4:5], s26, v0, v[68:69]
	v_lshl_add_u64 v[2:3], v[2:3], 0, v[72:73]
	v_cvt_pk_bf16_f32 v4, v30, v31
	v_cvt_pk_bf16_f32 v5, v32, v33
	v_mov_b32_e32 v100, v4
	v_mov_b32_e32 v101, v5
	v_cvt_pk_bf16_f32 v4, v26, v27
	v_cvt_pk_bf16_f32 v5, v28, v29
	v_mov_b32_e32 v102, v4
	v_mov_b32_e32 v103, v5
	v_lshl_add_u64 v[108:109], v[2:3], 0, v[110:111]
	s_nop 0
	v_permlane16_swap_b32_e32 v100, v102
	v_permlane16_swap_b32_e32 v101, v103
	global_store_dwordx4 v[108:109], v[100:103], off
	v_cvt_pk_bf16_f32 v4, v18, v19
	v_cvt_pk_bf16_f32 v5, v20, v21
	v_mov_b32_e32 v104, v4
	v_mov_b32_e32 v105, v5
	v_cvt_pk_bf16_f32 v4, v14, v15
	v_cvt_pk_bf16_f32 v5, v16, v17
	v_or_b32_e32 v0, 32, v66
	v_mov_b32_e32 v106, v4
	v_mov_b32_e32 v107, v5
	v_lshl_add_u64 v[108:109], v[2:3], 0, v[110:111]
	s_nop 0
	v_permlane16_swap_b32_e32 v104, v106
	v_permlane16_swap_b32_e32 v105, v107
	global_store_dwordx4 v[108:109], v[104:107], off offset:64
	v_mad_i64_i32 v[2:3], s[4:5], s26, v0, v[68:69]
	v_lshl_add_u64 v[2:3], v[2:3], 0, v[72:73]
	v_cvt_pk_bf16_f32 v4, v46, v47
	v_cvt_pk_bf16_f32 v5, v48, v49
	v_mov_b32_e32 v100, v4
	v_mov_b32_e32 v101, v5
	v_cvt_pk_bf16_f32 v4, v42, v43
	v_cvt_pk_bf16_f32 v5, v44, v45
	v_mov_b32_e32 v102, v4
	v_mov_b32_e32 v103, v5
	v_lshl_add_u64 v[108:109], v[2:3], 0, v[110:111]
	s_nop 0
	v_permlane16_swap_b32_e32 v100, v102
	v_permlane16_swap_b32_e32 v101, v103
	global_store_dwordx4 v[108:109], v[100:103], off
	v_cvt_pk_bf16_f32 v4, v38, v39
	v_cvt_pk_bf16_f32 v5, v40, v41
	v_mov_b32_e32 v104, v4
	v_mov_b32_e32 v105, v5
	v_cvt_pk_bf16_f32 v4, v34, v35
	v_cvt_pk_bf16_f32 v5, v36, v37
	v_or_b32_e32 v0, 48, v66
	v_mov_b32_e32 v106, v4
	v_mov_b32_e32 v107, v5
	v_lshl_add_u64 v[108:109], v[2:3], 0, v[110:111]
	s_nop 0
	v_permlane16_swap_b32_e32 v104, v106
	v_permlane16_swap_b32_e32 v105, v107
	global_store_dwordx4 v[108:109], v[104:107], off offset:64
	v_mad_i64_i32 v[2:3], s[4:5], s26, v0, v[68:69]
	v_lshl_add_u64 v[2:3], v[2:3], 0, v[72:73]
	v_cvt_pk_bf16_f32 v4, v62, v63
	v_cvt_pk_bf16_f32 v5, v64, v65
	v_mov_b32_e32 v100, v4
	v_mov_b32_e32 v101, v5
	v_cvt_pk_bf16_f32 v4, v58, v59
	v_cvt_pk_bf16_f32 v5, v60, v61
	v_mov_b32_e32 v102, v4
	v_mov_b32_e32 v103, v5
	v_lshl_add_u64 v[108:109], v[2:3], 0, v[110:111]
	s_nop 0
	v_permlane16_swap_b32_e32 v100, v102
	v_permlane16_swap_b32_e32 v101, v103
	global_store_dwordx4 v[108:109], v[100:103], off
	v_cvt_pk_bf16_f32 v4, v54, v55
	v_cvt_pk_bf16_f32 v5, v56, v57
	v_mov_b32_e32 v104, v4
	v_mov_b32_e32 v105, v5
	v_cvt_pk_bf16_f32 v4, v50, v51
	v_cvt_pk_bf16_f32 v5, v52, v53
	v_mov_b32_e32 v106, v4
	v_mov_b32_e32 v107, v5
	v_lshl_add_u64 v[108:109], v[2:3], 0, v[110:111]
	s_nop 0
	v_permlane16_swap_b32_e32 v104, v106
	v_permlane16_swap_b32_e32 v105, v107
	global_store_dwordx4 v[108:109], v[104:107], off offset:64
